# adds: loop-invariant gain parameter loads of prep1/prep2 hoisted out of the token loops
# baseline (speedup 1.0000x reference)
.LBB0_551:
	s_or_b64 exec, exec, s[0:1]
	v_mov_b32_e32 v20, v207
	s_waitcnt lgkmcnt(0)
	s_barrier
	v_readlane_b32 s1, v252, 34
	v_readfirstlane_b32 s0, v20
	s_ashr_i32 s0, s0, 6
	s_add_i32 s20, s0, s1
	s_cmp_gt_i32 s20, 0x107ff
	s_cbranch_scc1 .LBB0_568
	v_and_b32_e32 v22, 63, v20
	v_readlane_b32 s0, v252, 18
	v_lshlrev_b32_e32 v32, 3, v22
	v_readlane_b32 s1, v252, 19
	v_readlane_b32 s2, v252, 20
	v_readlane_b32 s3, v252, 21
	v_readlane_b32 s4, v252, 22
	v_readlane_b32 s5, v252, 23
	v_readlane_b32 s6, v252, 24
	v_readlane_b32 s7, v252, 25
	v_readlane_b32 s8, v252, 26
	v_readlane_b32 s9, v252, 27
	v_readlane_b32 s10, v252, 28
	v_readlane_b32 s11, v252, 29
	v_readlane_b32 s12, v252, 30
	v_readlane_b32 s13, v252, 31
	v_readlane_b32 s14, v252, 32
	v_readlane_b32 s15, v252, 33
	v_lshlrev_b32_e32 v30, 4, v22
	v_and_b32_e32 v23, 7, v20
	global_load_dwordx2 v[14:15], v32, s[10:11]
	global_load_dwordx4 v[2:5], v30, s[8:9]
	v_and_b32_e32 v25, 31, v20
	v_readlane_b32 s0, v252, 35
	v_lshlrev_b32_e32 v6, 3, v25
	v_readlane_b32 s8, v252, 43
	v_readlane_b32 s9, v252, 44
	v_readlane_b32 s10, v252, 45
	v_readlane_b32 s11, v252, 46
	v_lshlrev_b32_e32 v10, 5, v23
	v_cvt_f32_ubyte0_e32 v1, v23
	v_mul_f32_e32 v18, 0xbfd49a78, v1
	v_and_b32_e32 v1, 15, v20
	v_lshlrev_b32_e32 v34, 2, v22
	global_load_dwordx2 v[16:17], v6, s[10:11]
	s_nop 0
	global_load_dwordx4 v[6:9], v10, s[8:9] offset:16
	s_nop 0
	global_load_dwordx4 v[10:13], v10, s[8:9]
	v_cvt_f32_ubyte0_e32 v1, v1
	v_and_b32_e32 v24, 12, v34
	v_mul_f32_e32 v19, 0xbf549a78, v1
	v_cvt_f32_ubyte0_e32 v1, v24
	v_or_b32_e32 v21, 1, v24
	v_or_b32_e32 v26, 2, v24
	v_or_b32_e32 v24, 3, v24
	v_cvt_f32_ubyte0_e32 v24, v24
	v_exp_f32_e32 v46, v18
	v_mbcnt_hi_u32_b32 v18, -1, v232
	v_mul_f32_e32 v24, 0xbf549a78, v24
	v_exp_f32_e32 v47, v19
	v_and_b32_e32 v19, 64, v18
	v_exp_f32_e32 v45, v24
	v_add_u32_e32 v19, 64, v19
	v_xor_b32_e32 v24, 1, v18
	v_cmp_lt_i32_e32 vcc, v24, v19
	v_readlane_b32 s8, v252, 63
	v_readlane_b32 s1, v252, 36
	v_cndmask_b32_e32 v24, v18, v24, vcc
	v_lshlrev_b32_e32 v48, 2, v24
	v_xor_b32_e32 v24, 2, v18
	v_cmp_lt_i32_e32 vcc, v24, v19
	v_readlane_b32 s2, v252, 37
	v_readlane_b32 s3, v252, 38
	v_cndmask_b32_e32 v24, v18, v24, vcc
	v_lshlrev_b32_e32 v49, 2, v24
	v_xor_b32_e32 v24, 4, v18
	v_cmp_lt_i32_e32 vcc, v24, v19
	v_readlane_b32 s6, v252, 41
	v_readlane_b32 s7, v252, 42
	v_cndmask_b32_e32 v24, v18, v24, vcc
	v_lshlrev_b32_e32 v50, 2, v24
	v_xor_b32_e32 v24, 8, v18
	v_cmp_lt_i32_e32 vcc, v24, v19
	v_mov_b32_e32 v35, v0
	v_mov_b32_e32 v33, v0
	v_cndmask_b32_e32 v24, v18, v24, vcc
	v_lshlrev_b32_e32 v51, 2, v24
	v_xor_b32_e32 v24, 16, v18
	v_cmp_lt_i32_e32 vcc, v24, v19
	v_readlane_b32 s9, v253, 0
	s_ashr_i32 s21, s20, 31
	v_cndmask_b32_e32 v24, v18, v24, vcc
	v_lshlrev_b32_e32 v52, 2, v24
	v_xor_b32_e32 v24, 32, v18
	v_cmp_lt_i32_e32 vcc, v24, v19
	v_cmp_gt_u32_e64 s[0:1], 16, v22
	v_cmp_gt_u32_e64 s[2:3], 8, v22
	v_cndmask_b32_e32 v18, v18, v24, vcc
	v_lshlrev_b32_e32 v53, 2, v18
	v_lshl_add_u64 v[18:19], s[6:7], 0, v[32:33]
	v_cmp_gt_u32_e64 s[6:7], 4, v23
	v_lshl_add_u64 v[22:23], s[8:9], 0, v[34:35]
	s_lshl_b64 s[8:9], s[20:21], 10
	s_add_u32 s8, s8, 0x32a22000
	s_addc_u32 s9, s9, 0
	s_mul_i32 s11, s20, 0x300
	v_readlane_b32 s4, v252, 39
	v_readlane_b32 s5, v252, 40
	v_cvt_f32_ubyte0_e32 v26, v26
	v_or_b32_e32 v24, s8, v30
	s_mul_hi_i32 s10, s20, 0x300
	s_add_u32 s8, s11, 0x1cfa2100
	v_mul_f32_e32 v26, 0xbf549a78, v26
	v_bfe_u32 v54, v20, 5, 1
	v_lshlrev_b32_e32 v20, 1, v25
	v_cmp_gt_u32_e64 s[4:5], 16, v25
	v_mov_b32_e32 v25, s9
	s_addc_u32 s9, s10, 0
	v_exp_f32_e32 v44, v26
	v_lshl_add_u64 v[26:27], s[8:9], 0, v[32:33]
	s_add_u32 s8, s11, 0x1cfa2000
	v_cvt_f32_ubyte0_e32 v21, v21
	s_addc_u32 s9, s10, 0
	s_mul_i32 s11, s20, 0xa00
	v_mul_f32_e32 v1, 0xbf549a78, v1
	v_mul_f32_e32 v21, 0xbf549a78, v21
	v_or_b32_e32 v28, s8, v34
	s_mul_hi_i32 s10, s20, 0xa00
	s_add_u32 s8, s11, 0xe8a2540
	v_exp_f32_e32 v1, v1
	v_exp_f32_e32 v21, v21
	v_mov_b32_e32 v31, v0
	v_mov_b32_e32 v29, s9
	s_addc_u32 s9, s10, 0
	v_lshl_add_u64 v[30:31], s[8:9], 0, v[30:31]
	s_add_u32 s8, s11, 0xe8a2340
	s_addc_u32 s9, s10, 0
	v_lshl_add_u64 v[32:33], s[8:9], 0, v[32:33]
	v_or_b32_e32 v34, s11, v34
	v_mov_b32_e32 v35, s10
	v_readlane_b32 s12, v252, 47
	v_readlane_b32 s13, v252, 48
	v_readlane_b32 s14, v252, 49
	v_readlane_b32 s15, v252, 50
	s_mov_b64 s[98:99], exec
	s_and_b64 exec, exec, s[0:1]
	global_load_dwordx2 v[112:113], v[18:19], off
	s_mov_b64 exec, s[98:99]
	s_waitcnt vmcnt(0)
	s_branch .LBB0_554

.LBB0_560:
	s_or_b64 exec, exec, s[8:9]
	v_pk_mul_f32 v[40:41], v[38:39], v[38:39]
	v_cndmask_b32_e64 v42, 0, 1, s[14:15]
	v_add_f32_e32 v40, v40, v41
	ds_bpermute_b32 v41, v48, v40
	v_cmp_ne_u32_e64 s[8:9], 1, v42
	s_waitcnt lgkmcnt(0)
	v_add_f32_e32 v40, v40, v41
	ds_bpermute_b32 v41, v49, v40
	s_waitcnt lgkmcnt(0)
	v_add_f32_e32 v40, v40, v41
	ds_bpermute_b32 v41, v50, v40
	s_waitcnt lgkmcnt(0)
	v_add_f32_e32 v40, v40, v41
	ds_bpermute_b32 v41, v51, v40
	s_waitcnt lgkmcnt(0)
	v_add_f32_e32 v40, v40, v41
	ds_bpermute_b32 v41, v52, v40
	s_waitcnt lgkmcnt(0)
	v_add_f32_e32 v40, v40, v41
	ds_bpermute_b32 v41, v53, v40
	s_waitcnt vmcnt(2)
	s_and_saveexec_b64 s[14:15], s[0:1]
	s_cbranch_execz .LBB0_564
	v_mov_b32_e32 v42, v112
	v_mov_b32_e32 v43, v113
	s_waitcnt lgkmcnt(0)
	v_add_f32_e32 v40, v40, v41
	v_fmamk_f32 v40, v40, 0x3d000000, v206
	v_mul_f32_e32 v41, 0x4b800000, v40
	v_cmp_gt_f32_e32 vcc, s97, v40
	s_nop 1
	v_cndmask_b32_e32 v40, v40, v41, vcc
	v_rsq_f32_e32 v40, v40
	s_nop 0
	v_mul_f32_e32 v41, 0x45800000, v40
	v_cndmask_b32_e32 v40, v40, v41, vcc
	s_and_b64 vcc, exec, s[8:9]
	v_pk_mul_f32 v[40:41], v[40:41], v[42:43] op_sel_hi:[0,1]
	v_pk_mul_f32 v[38:39], v[38:39], v[40:41]
	s_cbranch_vccnz .LBB0_563
	v_cndmask_b32_e64 v40, v56, v55, s[2:3]
	v_mul_f32_e32 v40, v46, v40
	v_mul_f32_e32 v41, 0.15915494, v40
	v_sin_f32_e32 v40, v41
	v_cos_f32_e32 v42, v41
	v_pk_mul_f32 v[40:41], v[40:41], v[38:39] op_sel:[0,1] op_sel_hi:[0,0]
	v_pk_mul_f32 v[58:59], v[42:43], v[38:39] op_sel_hi:[0,1]
	v_pk_fma_f32 v[38:39], v[42:43], v[38:39], v[40:41] op_sel_hi:[0,1,1]
	v_sub_f32_e32 v38, v58, v40

.LBB0_693:
	s_or_b64 exec, exec, s[0:1]
	s_waitcnt lgkmcnt(0)
	v_mov_b32_e32 v2, v207
	s_barrier
	v_readlane_b32 s1, v252, 34
	v_readfirstlane_b32 s0, v2
	s_ashr_i32 s0, s0, 6
	s_add_i32 s8, s0, s1
	s_cmp_gt_i32 s8, 0x107ff
	s_cbranch_scc1 .LBB0_707
	v_lshlrev_b32_e32 v3, 1, v2
	v_and_b32_e32 v3, 6, v3
	v_cvt_f32_ubyte0_e32 v4, v3
	v_or_b32_e32 v3, 1, v3
	v_cvt_f32_ubyte0_e32 v3, v3
	v_mul_f32_e32 v3, 0xbfd49a78, v3
	v_mbcnt_hi_u32_b32 v5, -1, v232
	v_mul_f32_e32 v4, 0xbfd49a78, v4
	v_exp_f32_e32 v55, v3
	v_and_b32_e32 v3, 64, v5
	v_and_b32_e32 v16, 63, v2
	v_bfe_u32 v1, v2, 3, 3
	v_exp_f32_e32 v54, v4
	v_and_b32_e32 v4, 7, v2
	v_xor_b32_e32 v2, 1, v5
	v_add_u32_e32 v8, 64, v3
	v_cmp_lt_i32_e32 vcc, v2, v8
	v_readlane_b32 s64, v252, 35
	v_readlane_b32 s4, v253, 1
	v_cndmask_b32_e32 v2, v5, v2, vcc
	v_lshlrev_b32_e32 v56, 2, v2
	v_xor_b32_e32 v2, 2, v5
	v_cmp_lt_i32_e32 vcc, v2, v8
	v_mov_b32_e32 v3, v0
	v_readlane_b32 s68, v252, 39
	v_cndmask_b32_e32 v2, v5, v2, vcc
	v_lshlrev_b32_e32 v57, 2, v2
	v_lshlrev_b32_e32 v2, 6, v4
	v_readlane_b32 s69, v252, 40
	v_lshlrev_b32_e32 v6, 5, v4
	v_mov_b32_e32 v7, v0
	v_readlane_b32 s5, v253, 2
	v_lshl_add_u64 v[22:23], s[68:69], 0, v[2:3]
	v_xor_b32_e32 v2, 4, v5
	v_lshl_add_u64 v[20:21], s[4:5], 0, v[6:7]
	v_readlane_b32 s4, v252, 63
	v_cmp_lt_i32_e32 vcc, v2, v8
	v_lshlrev_b32_e32 v17, 4, v4
	v_readlane_b32 s65, v252, 36
	v_readlane_b32 s66, v252, 37
	v_readlane_b32 s67, v252, 38
	v_readlane_b32 s5, v253, 0
	v_cndmask_b32_e32 v2, v5, v2, vcc
	v_cmp_gt_u32_e64 s[0:1], 4, v4
	v_cmp_lt_u32_e64 s[2:3], 3, v4
	v_lshl_add_u64 v[24:25], s[4:5], 0, v[6:7]
	v_lshlrev_b32_e32 v18, 3, v4
	v_lshlrev_b32_e32 v58, 2, v2
	global_load_dwordx4 v[2:5], v6, s[64:65]
	s_nop 0
	global_load_dwordx4 v[6:9], v6, s[64:65] offset:16
	s_mul_i32 s5, s8, 0x600
	global_load_dwordx4 v[10:13], v17, s[66:67]
	s_mul_hi_i32 s4, s8, 0x600
	s_add_u32 s6, s5, 0x20122080
	v_mul_u32_u24_e32 v14, 0x60, v1
	s_addc_u32 s7, s4, 0
	v_lshlrev_b32_e32 v14, 1, v14
	v_mov_b32_e32 v15, v0
	s_add_u32 s5, s5, 0x20122000
	s_addc_u32 s4, s4, 0
	s_movk_i32 s64, 0x2100
	s_mov_b32 s12, 0x3e16c740
	v_readlane_b32 s70, v252, 41
	v_readlane_b32 s71, v252, 42
	v_readlane_b32 s72, v252, 43
	v_readlane_b32 s73, v252, 44
	v_readlane_b32 s74, v252, 45
	v_readlane_b32 s75, v252, 46
	v_readlane_b32 s76, v252, 47
	v_readlane_b32 s77, v252, 48
	v_readlane_b32 s78, v252, 49
	v_readlane_b32 s79, v252, 50
	s_waitcnt vmcnt(0)
	v_mov_b32_e32 v26, v11
	v_mov_b32_e32 v27, v13
	v_mov_b32_e32 v11, v12
	v_or_b32_e32 v12, s6, v18
	v_mov_b32_e32 v13, s7
	v_lshl_add_u64 v[28:29], v[12:13], 0, v[14:15]
	v_or_b32_e32 v12, s5, v17
	s_mul_i32 s5, s8, 0xe00
	v_mov_b32_e32 v13, s4
	s_mul_hi_i32 s4, s8, 0xe00
	s_add_u32 s6, s5, 0xe8a2880
	s_addc_u32 s7, s4, 0
	s_add_u32 s5, s5, 0xe8a2800
	v_lshl_add_u64 v[30:31], v[12:13], 0, v[14:15]
	v_or_b32_e32 v12, s6, v18
	v_mov_b32_e32 v13, s7
	s_addc_u32 s4, s4, 0
	v_lshl_add_u64 v[32:33], v[12:13], 0, v[14:15]
	v_or_b32_e32 v12, s5, v17
	v_mov_b32_e32 v13, s4
	v_lshl_add_u64 v[34:35], v[12:13], 0, v[14:15]
	v_lshlrev_b32_e32 v12, 5, v16
	v_mov_b32_e32 v13, v0
	v_mov_b32_e32 v14, 0xe00
	v_mad_i64_i32 v[36:37], s[4:5], s8, v14, v[12:13]
	s_mov_b64 s[98:99], exec
	s_and_b64 exec, exec, s[0:1]
	global_load_dwordx4 v[110:113], v[22:23], off offset:48
	global_load_dwordx4 v[114:117], v[22:23], off offset:32
	global_load_dwordx4 v[118:121], v[22:23], off offset:16
	global_load_dwordx4 v[122:125], v[22:23], off
	s_mov_b64 exec, s[98:99]
	s_waitcnt vmcnt(0)
	s_branch .LBB0_696

.LBB0_702:
	s_andn2_saveexec_b64 s[4:5], s[4:5]
	s_cbranch_execz .LBB0_704
	s_waitcnt lgkmcnt(0)
	v_add_f32_e32 v12, v62, v63
	v_fmamk_f32 v12, v12, 0x3c800000, v206
	v_cmp_gt_f32_e32 vcc, s97, v12
	v_mul_f32_e32 v13, 0x4b800000, v12
	s_nop 0
	v_cndmask_b32_e32 v12, v12, v13, vcc
	v_rsq_f32_e32 v12, v12
	s_nop 0
	v_mul_f32_e32 v13, 0x45800000, v12
	v_cndmask_b32_e32 v70, v12, v13, vcc
	v_mov_b32_e32 v62, v110
	v_mov_b32_e32 v63, v111
	v_mov_b32_e32 v64, v112
	v_mov_b32_e32 v65, v113
	v_mov_b32_e32 v16, v114
	v_mov_b32_e32 v17, v115
	v_mov_b32_e32 v18, v116
	v_mov_b32_e32 v19, v117
	v_mov_b32_e32 v66, v118
	v_mov_b32_e32 v67, v119
	v_mov_b32_e32 v68, v120
	v_mov_b32_e32 v69, v121
	v_mov_b32_e32 v12, v122
	v_mov_b32_e32 v13, v123
	v_mov_b32_e32 v14, v124
	v_mov_b32_e32 v15, v125
	v_pk_mul_f32 v[38:39], v[70:71], v[38:39] op_sel_hi:[0,1]
	v_pk_mul_f32 v[52:53], v[70:71], v[52:53] op_sel_hi:[0,1]
	v_pk_mul_f32 v[50:51], v[70:71], v[50:51] op_sel_hi:[0,1]
	v_pk_mul_f32 v[46:47], v[70:71], v[46:47] op_sel_hi:[0,1]
	v_pk_mul_f32 v[16:17], v[38:39], v[16:17]
	v_pk_mul_f32 v[38:39], v[70:71], v[40:41] op_sel_hi:[0,1]
	v_pk_mul_f32 v[18:19], v[38:39], v[18:19]
	v_cvt_pk_bf16_f32 v16, v16, v17
	v_cvt_pk_bf16_f32 v17, v18, v19
	v_pk_mul_f32 v[18:19], v[70:71], v[42:43] op_sel_hi:[0,1]
	v_pk_mul_f32 v[38:39], v[70:71], v[44:45] op_sel_hi:[0,1]
	v_pk_mul_f32 v[18:19], v[18:19], v[62:63]
	v_pk_mul_f32 v[38:39], v[38:39], v[64:65]
	v_pk_mul_f32 v[12:13], v[52:53], v[12:13]
	v_pk_mul_f32 v[14:15], v[50:51], v[14:15]
	v_cvt_pk_bf16_f32 v18, v18, v19
	v_cvt_pk_bf16_f32 v19, v38, v39
	v_mov_b32_e32 v38, s9
	v_mov_b32_e32 v39, v0
	v_cvt_pk_bf16_f32 v12, v12, v13
	v_cvt_pk_bf16_f32 v13, v14, v15
	v_pk_mul_f32 v[14:15], v[70:71], v[48:49] op_sel_hi:[0,1]
	v_mad_i64_i32 v[38:39], s[10:11], v61, s64, v[38:39]
	s_movk_i32 s9, 0xc0
	v_pk_mul_f32 v[14:15], v[14:15], v[66:67]
	v_pk_mul_f32 v[46:47], v[46:47], v[68:69]
	v_mad_u64_u32 v[40:41], s[10:11], v38, s9, v[24:25]
	v_cvt_pk_bf16_f32 v14, v14, v15
	v_cvt_pk_bf16_f32 v15, v46, v47
	v_mad_i32_i24 v41, v39, s9, v41
	global_store_dwordx4 v[40:41], v[12:15], off
	global_store_dwordx4 v[40:41], v[16:19], off offset:16
.LBB0_704:
	s_or_b64 exec, exec, s[4:5]
	s_waitcnt vmcnt(4)
	v_mov_b32_e32 v12, v102
	v_mov_b32_e32 v13, v103
	v_mov_b32_e32 v14, v104
	v_mov_b32_e32 v15, v105
	v_mov_b32_e32 v44, v106
	v_mov_b32_e32 v45, v107
	s_mov_b32 s4, 0x3d000000
	s_mov_b32 s5, 0x3c800000
	v_lshl_add_u64 v[42:43], s[50:51], 0, v[30:31]
	v_and_b32_e32 v41, 0xffff0000, v12
	v_and_b32_e32 v19, 0xffff0000, v15
	v_and_b32_e32 v18, s0, v14
	v_lshlrev_b32_e32 v40, 16, v12
	v_mul_f32_e32 v12, v41, v41
	v_lshlrev_b32_e32 v16, 16, v15
	v_mov_b32_e32 v17, v19
	v_pk_mul_f32 v[18:19], v[18:19], v[18:19]
	v_lshlrev_b32_e32 v38, 16, v14
	v_and_b32_e32 v39, 0xffff0000, v14
	v_lshlrev_b32_e32 v14, 16, v13
	v_and_b32_e32 v15, 0xffff0000, v13
	v_pk_fma_f32 v[12:13], v[40:41], v[40:41], v[12:13] op_sel_hi:[1,1,0]
	v_mul_f32_e32 v18, v15, v15
	v_pk_fma_f32 v[12:13], v[14:15], v[14:15], v[12:13]
	v_lshlrev_b32_e32 v47, 16, v45
	v_pk_add_f32 v[12:13], v[18:19], v[12:13] op_sel_hi:[0,1]
	v_pk_fma_f32 v[12:13], v[38:39], v[38:39], v[12:13]
	v_mul_f32_e32 v18, v39, v39
	v_lshlrev_b32_e32 v46, 16, v44
	v_and_b32_e32 v45, 0xffff0000, v45
	v_and_b32_e32 v44, 0xffff0000, v44
	v_pk_add_f32 v[12:13], v[18:19], v[12:13] op_sel_hi:[0,1]
	v_pk_mul_f32 v[48:49], v[44:45], v[44:45]
	v_pk_fma_f32 v[12:13], v[16:17], v[16:17], v[12:13]
	v_pk_fma_f32 v[48:49], v[46:47], v[46:47], v[48:49]
	s_nop 0
	v_mov_b32_e32 v18, v48
	v_pk_mov_b32 v[12:13], v[48:49], v[12:13] op_sel:[1,0]
	s_nop 0
	v_pk_add_f32 v[12:13], v[18:19], v[12:13]
	ds_bpermute_b32 v19, v56, v13
	ds_bpermute_b32 v18, v56, v12
	s_waitcnt lgkmcnt(0)
	v_pk_add_f32 v[12:13], v[12:13], v[18:19]
	ds_bpermute_b32 v19, v57, v13
	ds_bpermute_b32 v18, v57, v12
	s_waitcnt lgkmcnt(0)
	v_pk_add_f32 v[12:13], v[12:13], v[18:19]
	ds_bpermute_b32 v19, v58, v13
	ds_bpermute_b32 v18, v58, v12
	s_waitcnt lgkmcnt(0)
	v_pk_add_f32 v[12:13], v[12:13], v[18:19]
	s_nop 0
	v_pk_fma_f32 v[18:19], v[12:13], s[4:5], v[206:207] op_sel_hi:[1,1,0]
	s_nop 0
	v_mul_f32_e32 v12, 0x4b800000, v19
	v_cmp_gt_f32_e64 s[4:5], s97, v19
	v_cmp_gt_f32_e32 vcc, s97, v18
	s_nop 0
	v_cndmask_b32_e64 v12, v19, v12, s[4:5]
	v_rsq_f32_e32 v12, v12
	s_nop 0
	v_mul_f32_e32 v13, 0x45800000, v12
	v_cndmask_b32_e64 v12, v12, v13, s[4:5]
	v_mul_f32_e32 v48, 0x3e16c740, v12
	v_pk_mul_f32 v[12:13], v[48:49], v[40:41] op_sel_hi:[0,1]
	v_pk_mul_f32 v[14:15], v[48:49], v[14:15] op_sel_hi:[0,1]
	v_pk_mul_f32 v[12:13], v[2:3], v[12:13]
	v_pk_mul_f32 v[14:15], v[4:5], v[14:15]
	v_cvt_pk_bf16_f32 v12, v12, v13
	v_cvt_pk_bf16_f32 v13, v14, v15
	v_pk_mul_f32 v[14:15], v[48:49], v[38:39] op_sel_hi:[0,1]
	v_pk_mul_f32 v[16:17], v[48:49], v[16:17] op_sel_hi:[0,1]
	v_pk_mul_f32 v[14:15], v[6:7], v[14:15]
	v_pk_mul_f32 v[16:17], v[8:9], v[16:17]
	v_cvt_pk_bf16_f32 v14, v14, v15
	v_cvt_pk_bf16_f32 v15, v16, v17
	global_store_dwordx4 v[42:43], v[12:15], off
	s_nop 1
	v_mul_f32_e32 v12, 0x4b800000, v18
	v_cndmask_b32_e32 v12, v18, v12, vcc
	v_rsq_f32_e32 v12, v12
	s_nop 0
	v_mul_f32_e32 v13, 0x45800000, v12
	v_cndmask_b32_e32 v12, v12, v13, vcc
	v_pk_mul_f32 v[14:15], v[10:11], v[12:13] op_sel_hi:[1,0]
	v_pk_mul_f32 v[12:13], v[26:27], v[12:13] op_sel_hi:[1,0]
	v_pk_mul_f32 v[14:15], v[14:15], v[46:47]
	v_pk_mul_f32 v[12:13], v[12:13], v[44:45]
	s_andn2_b64 vcc, exec, s[6:7]
	s_cbranch_vccnz .LBB0_695
	v_cndmask_b32_e64 v17, v60, v59, s[0:1]
	v_mul_f32_e32 v16, v54, v17
	v_mul_f32_e32 v17, v55, v17
	v_mul_f32_e32 v18, 0.15915494, v16
	v_mul_f32_e32 v19, 0.15915494, v17
	v_sin_f32_e32 v16, v18
	v_sin_f32_e32 v17, v19
	v_cos_f32_e32 v18, v18
	v_cos_f32_e32 v19, v19
	v_pk_mul_f32 v[38:39], v[16:17], v[12:13]
	s_nop 0
	v_pk_fma_f32 v[38:39], v[18:19], v[14:15], v[38:39] neg_lo:[0,0,1] neg_hi:[0,0,1]
	v_pk_mul_f32 v[12:13], v[18:19], v[12:13]
	s_nop 0
	v_pk_fma_f32 v[12:13], v[16:17], v[14:15], v[12:13]
	v_mov_b64_e32 v[14:15], v[38:39]
	s_branch .LBB0_695
